# indexer threshold loops: cross-row count reduction via row_bcast DPP; GEMM loop counter/test moved ahead of the closing barrier
# speedup vs baseline: 1.0074x; 1.0032x over previous
.Lg1_skip:
	ds_read_b64 v[68:69], v220 offset:18432
	ds_read_b64 v[70:71], v221 offset:18432
	ds_read_b64 v[84:85], v224 offset:55296
	ds_read_b64 v[86:87], v225 offset:55296
	ds_read_b64 v[88:89], v224 offset:57344
	ds_read_b64 v[90:91], v225 offset:57344
	ds_read_b64 v[92:93], v224 offset:59392
	ds_read_b64 v[94:95], v225 offset:59392
	ds_read_b64 v[158:159], v224 offset:61440
	ds_read_b64 v[160:161], v225 offset:61440
	ds_read_b64 v[72:73], v220 offset:20480
	ds_read_b64 v[74:75], v221 offset:20480
	ds_read_b64 v[76:77], v220 offset:22528
	ds_read_b64 v[78:79], v221 offset:22528
	s_waitcnt lgkmcnt(12)
	s_waitcnt lgkmcnt(10)
	v_mfma_f32_16x16x32_bf16 v[44:47], v[68:71], v[84:87], v[44:47]
	ds_read_b64 v[80:81], v220 offset:24576
	ds_read_b64 v[82:83], v221 offset:24576
	ds_read_b64 v[162:163], v222 offset:18432
	ds_read_b64 v[164:165], v223 offset:18432
	s_waitcnt lgkmcnt(12)
	v_mfma_f32_16x16x32_bf16 v[52:55], v[68:71], v[88:91], v[52:55]
	ds_read_b64 v[178:179], v226 offset:55296
	ds_read_b64 v[180:181], v227 offset:55296
	s_waitcnt lgkmcnt(12)
	v_mfma_f32_16x16x32_bf16 v[60:63], v[68:71], v[92:95], v[60:63]
	ds_read_b64 v[182:183], v226 offset:57344
	ds_read_b64 v[184:185], v227 offset:57344
	s_waitcnt lgkmcnt(12)
	v_mfma_f32_16x16x32_bf16 v[56:59], v[68:71], v[158:161], v[56:59]
	ds_read_b64 v[186:187], v226 offset:59392
	ds_read_b64 v[188:189], v227 offset:59392
	s_waitcnt lgkmcnt(12)
	v_mfma_f32_16x16x32_bf16 v[40:43], v[72:75], v[84:87], v[40:43]
	ds_read_b64 v[190:191], v226 offset:61440
	ds_read_b64 v[192:193], v227 offset:61440
	v_mfma_f32_16x16x32_bf16 v[36:39], v[72:75], v[88:91], v[36:39]
	v_mfma_f32_16x16x32_bf16 v[32:35], v[72:75], v[92:95], v[32:35]
	v_mfma_f32_16x16x32_bf16 v[28:31], v[72:75], v[158:161], v[28:31]
	s_waitcnt lgkmcnt(12)
	v_mfma_f32_16x16x32_bf16 v[24:27], v[76:79], v[84:87], v[24:27]
	ds_read_b64 v[166:167], v222 offset:20480
	ds_read_b64 v[168:169], v223 offset:20480
	v_mfma_f32_16x16x32_bf16 v[20:23], v[76:79], v[88:91], v[20:23]
	v_mfma_f32_16x16x32_bf16 v[16:19], v[76:79], v[92:95], v[16:19]
	v_mfma_f32_16x16x32_bf16 v[12:15], v[76:79], v[158:161], v[12:15]
	s_waitcnt lgkmcnt(12)
	v_mfma_f32_16x16x32_bf16 v[8:11], v[80:83], v[84:87], v[8:11]
	ds_read_b64 v[170:171], v222 offset:22528
	ds_read_b64 v[172:173], v223 offset:22528
	v_mfma_f32_16x16x32_bf16 v[4:7], v[80:83], v[88:91], v[4:7]
	v_mfma_f32_16x16x32_bf16 v[0:3], v[80:83], v[92:95], v[0:3]
	v_mfma_f32_16x16x32_bf16 v[48:51], v[80:83], v[158:161], v[48:51]
	s_waitcnt lgkmcnt(12)
	s_waitcnt lgkmcnt(10)
	v_mfma_f32_16x16x32_bf16 v[44:47], v[162:165], v[178:181], v[44:47]
	ds_read_b64 v[174:175], v222 offset:24576
	ds_read_b64 v[176:177], v223 offset:24576
	s_waitcnt lgkmcnt(10)
	v_mfma_f32_16x16x32_bf16 v[52:55], v[162:165], v[182:185], v[52:55]
	s_waitcnt lgkmcnt(8)
	v_mfma_f32_16x16x32_bf16 v[60:63], v[162:165], v[186:189], v[60:63]
	s_waitcnt lgkmcnt(6)
	v_mfma_f32_16x16x32_bf16 v[56:59], v[162:165], v[190:193], v[56:59]
	s_waitcnt lgkmcnt(4)
	v_mfma_f32_16x16x32_bf16 v[40:43], v[166:169], v[178:181], v[40:43]
	v_mfma_f32_16x16x32_bf16 v[36:39], v[166:169], v[182:185], v[36:39]
	v_mfma_f32_16x16x32_bf16 v[32:35], v[166:169], v[186:189], v[32:35]
	v_mfma_f32_16x16x32_bf16 v[28:31], v[166:169], v[190:193], v[28:31]
	s_waitcnt lgkmcnt(2)
	v_mfma_f32_16x16x32_bf16 v[24:27], v[170:173], v[178:181], v[24:27]
	v_mfma_f32_16x16x32_bf16 v[20:23], v[170:173], v[182:185], v[20:23]
	v_mfma_f32_16x16x32_bf16 v[16:19], v[170:173], v[186:189], v[16:19]
	v_mfma_f32_16x16x32_bf16 v[12:15], v[170:173], v[190:193], v[12:15]
	s_waitcnt lgkmcnt(0)
	v_mfma_f32_16x16x32_bf16 v[8:11], v[174:177], v[178:181], v[8:11]
	v_mfma_f32_16x16x32_bf16 v[4:7], v[174:177], v[182:185], v[4:7]
	v_mfma_f32_16x16x32_bf16 v[0:3], v[174:177], v[186:189], v[0:3]
	v_mfma_f32_16x16x32_bf16 v[48:51], v[174:177], v[190:193], v[48:51]
	s_add_i32 s9, s9, 1
	s_cmp_lg_u32 s9, 8
	s_waitcnt vmcnt(0)
	s_barrier
	s_cbranch_scc1 .Lg1_loop
	s_setprio 0
	s_or_b32 s52, s49, s6
	s_cmp_gt_u32 s8, 31
	s_mov_b64 s[4:5], -1
	s_cbranch_scc0 .LBB0_220
	s_cmp_lt_u32 s8, 48
	s_cbranch_scc1 .LBB0_221
	s_cmp_lt_u32 s8, 56
	s_cbranch_scc1 .LBB0_225
	s_cmp_lt_u32 s8, 64
	s_cbranch_scc1 .LBB0_233
	s_cmpk_lt_u32 s8, 0x48
	s_cbranch_scc1 .LBB0_546
	s_cmpk_lt_u32 s8, 0x50
	s_cbranch_scc1 .LBB0_547
	s_cmpk_lt_u32 s8, 0x70
	s_cbranch_scc1 .LBB0_548
	s_cmpk_lt_u32 s8, 0x90
	s_cbranch_scc1 .LBB0_549
	s_cmpk_lt_u32 s8, 0x98
	s_cbranch_scc1 .LBB0_550
	s_cmpk_lt_u32 s8, 0xa0
	s_mov_b64 s[6:7], 0
	s_cbranch_scc1 .LBB0_551
	s_cmpk_lt_u32 s8, 0xb0
	s_mov_b64 s[30:31], 0
	s_cbranch_scc1 .LBB0_552
	s_cmpk_eq_i32 s52, 0xb00
	s_cbranch_scc1 .LBB0_553
	s_cmpk_lt_u32 s52, 0xd40
	s_cselect_b64 s[8:9], -1, 0
	s_cmpk_gt_u32 s52, 0xd3f
	s_cselect_b64 s[28:29], -1, 0
	s_mov_b64 s[26:27], 0
	s_branch .LBB0_554

.Lbq8_loop:
	v_subrev_u32_e32 v252, s60, v41
	v_subrev_u32_e32 v253, s60, v39
	v_alignbit_b32 v254, v254, v252, 31
	v_alignbit_b32 v255, v255, v253, 31
	v_subrev_u32_e32 v252, s60, v38
	v_subrev_u32_e32 v253, s60, v37
	v_alignbit_b32 v254, v254, v252, 31
	v_alignbit_b32 v255, v255, v253, 31
	v_subrev_u32_e32 v252, s60, v1
	v_subrev_u32_e32 v253, s60, v0
	v_alignbit_b32 v254, v254, v252, 31
	v_alignbit_b32 v255, v255, v253, 31
	v_subrev_u32_e32 v252, s60, v3
	v_subrev_u32_e32 v253, s60, v2
	v_alignbit_b32 v254, v254, v252, 31
	v_alignbit_b32 v255, v255, v253, 31
	v_subrev_u32_e32 v252, s60, v5
	v_subrev_u32_e32 v253, s60, v4
	v_alignbit_b32 v254, v254, v252, 31
	v_alignbit_b32 v255, v255, v253, 31
	v_subrev_u32_e32 v252, s60, v7
	v_subrev_u32_e32 v253, s60, v6
	v_alignbit_b32 v254, v254, v252, 31
	v_alignbit_b32 v255, v255, v253, 31
	v_subrev_u32_e32 v252, s60, v9
	v_subrev_u32_e32 v253, s60, v8
	v_alignbit_b32 v254, v254, v252, 31
	v_alignbit_b32 v255, v255, v253, 31
	v_subrev_u32_e32 v252, s60, v11
	v_subrev_u32_e32 v253, s60, v10
	v_alignbit_b32 v254, v254, v252, 31
	v_alignbit_b32 v255, v255, v253, 31
	v_subrev_u32_e32 v252, s60, v13
	v_subrev_u32_e32 v253, s60, v12
	v_alignbit_b32 v254, v254, v252, 31
	v_alignbit_b32 v255, v255, v253, 31
	v_subrev_u32_e32 v252, s60, v15
	v_subrev_u32_e32 v253, s60, v14
	v_alignbit_b32 v254, v254, v252, 31
	v_alignbit_b32 v255, v255, v253, 31
	v_subrev_u32_e32 v252, s60, v17
	v_subrev_u32_e32 v253, s60, v16
	v_alignbit_b32 v254, v254, v252, 31
	v_alignbit_b32 v255, v255, v253, 31
	v_subrev_u32_e32 v252, s60, v19
	v_subrev_u32_e32 v253, s60, v18
	v_alignbit_b32 v254, v254, v252, 31
	v_alignbit_b32 v255, v255, v253, 31
	v_subrev_u32_e32 v252, s60, v21
	v_subrev_u32_e32 v253, s60, v20
	v_alignbit_b32 v254, v254, v252, 31
	v_alignbit_b32 v255, v255, v253, 31
	v_subrev_u32_e32 v252, s60, v23
	v_subrev_u32_e32 v253, s60, v22
	v_alignbit_b32 v254, v254, v252, 31
	v_alignbit_b32 v255, v255, v253, 31
	v_subrev_u32_e32 v252, s60, v25
	v_subrev_u32_e32 v253, s60, v24
	v_alignbit_b32 v254, v254, v252, 31
	v_alignbit_b32 v255, v255, v253, 31
	v_subrev_u32_e32 v252, s60, v27
	v_subrev_u32_e32 v253, s60, v26
	v_alignbit_b32 v254, v254, v252, 31
	v_alignbit_b32 v255, v255, v253, 31
	v_subrev_u32_e32 v252, s60, v29
	v_subrev_u32_e32 v253, s60, v28
	v_alignbit_b32 v254, v254, v252, 31
	v_alignbit_b32 v255, v255, v253, 31
	v_subrev_u32_e32 v252, s60, v31
	v_subrev_u32_e32 v253, s60, v30
	v_alignbit_b32 v254, v254, v252, 31
	v_alignbit_b32 v255, v255, v253, 31
	v_subrev_u32_e32 v252, s60, v33
	v_subrev_u32_e32 v253, s60, v32
	v_alignbit_b32 v254, v254, v252, 31
	v_alignbit_b32 v255, v255, v253, 31
	v_subrev_u32_e32 v252, s60, v35
	v_subrev_u32_e32 v253, s60, v34
	v_alignbit_b32 v254, v254, v252, 31
	v_alignbit_b32 v255, v255, v253, 31
	v_subrev_u32_e32 v252, s60, v40
	v_subrev_u32_e32 v253, s60, v36
	v_alignbit_b32 v254, v254, v252, 31
	v_alignbit_b32 v255, v255, v253, 31
	v_subrev_u32_e32 v252, s60, v43
	v_subrev_u32_e32 v253, s60, v42
	v_alignbit_b32 v254, v254, v252, 31
	v_alignbit_b32 v255, v255, v253, 31
	v_subrev_u32_e32 v252, s60, v46
	v_subrev_u32_e32 v253, s60, v45
	v_alignbit_b32 v254, v254, v252, 31
	v_alignbit_b32 v255, v255, v253, 31
	v_subrev_u32_e32 v252, s60, v48
	v_subrev_u32_e32 v253, s60, v47
	v_alignbit_b32 v254, v254, v252, 31
	v_alignbit_b32 v255, v255, v253, 31
	v_subrev_u32_e32 v252, s60, v50
	v_subrev_u32_e32 v253, s60, v49
	v_alignbit_b32 v254, v254, v252, 31
	v_alignbit_b32 v255, v255, v253, 31
	v_subrev_u32_e32 v252, s60, v52
	v_subrev_u32_e32 v253, s60, v51
	v_alignbit_b32 v254, v254, v252, 31
	v_alignbit_b32 v255, v255, v253, 31
	v_subrev_u32_e32 v252, s60, v54
	v_subrev_u32_e32 v253, s60, v53
	v_alignbit_b32 v254, v254, v252, 31
	v_alignbit_b32 v255, v255, v253, 31
	v_subrev_u32_e32 v252, s60, v56
	v_subrev_u32_e32 v253, s60, v55
	v_alignbit_b32 v254, v254, v252, 31
	v_alignbit_b32 v255, v255, v253, 31
	v_subrev_u32_e32 v252, s60, v58
	v_subrev_u32_e32 v253, s60, v57
	v_alignbit_b32 v254, v254, v252, 31
	v_alignbit_b32 v255, v255, v253, 31
	v_subrev_u32_e32 v252, s60, v60
	v_subrev_u32_e32 v253, s60, v59
	v_alignbit_b32 v254, v254, v252, 31
	v_alignbit_b32 v255, v255, v253, 31
	v_subrev_u32_e32 v252, s60, v62
	v_subrev_u32_e32 v253, s60, v61
	v_alignbit_b32 v254, v254, v252, 31
	v_alignbit_b32 v255, v255, v253, 31
	v_subrev_u32_e32 v252, s60, v64
	v_subrev_u32_e32 v253, s60, v63
	v_alignbit_b32 v254, v254, v252, 31
	v_alignbit_b32 v255, v255, v253, 31
	v_bcnt_u32_b32 v251, v254, 0
	v_bcnt_u32_b32 v251, v255, v251
	s_nop 1
	v_add_u32_dpp v251, v251, v251 quad_perm:[1,0,3,2] row_mask:0xf bank_mask:0xf
	v_mov_b32_e32 v254, 0
	v_mov_b32_e32 v255, 0
	v_add_u32_dpp v251, v251, v251 quad_perm:[2,3,0,1] row_mask:0xf bank_mask:0xf
	s_nop 1
	v_add_u32_dpp v251, v251, v251 row_half_mirror row_mask:0xf bank_mask:0xf
	s_nop 1
	v_add_u32_dpp v251, v251, v251 row_mirror row_mask:0xf bank_mask:0xf
	s_nop 1
	v_add_u32_dpp v251, v251, v251 row_bcast:15 row_mask:0xa bank_mask:0xf
	s_nop 1
	v_add_u32_dpp v251, v251, v251 row_bcast:31 row_mask:0xc bank_mask:0xf
	s_nop 1
	v_readlane_b32 s30, v251, 63
	s_sub_i32 s30, 0x1000, s30
	s_cmpk_lt_u32 s30, 0x100
	s_cselect_b32 s58, s58, s60
	s_cmpk_eq_i32 s30, 0x100
	s_cbranch_scc1 .Lbq_exit
	s_sub_u32 s59, s59, 1
	s_cbranch_scc1 .Lbq_exit
	s_lshl_b32 s60, 1, s59
	s_or_b32 s60, s60, s58
	s_branch .Lbq8_loop
.Lbq7_loop:
	v_subrev_u32_e32 v252, s60, v41
	v_subrev_u32_e32 v253, s60, v39
	v_alignbit_b32 v254, v254, v252, 31
	v_alignbit_b32 v255, v255, v253, 31
	v_subrev_u32_e32 v252, s60, v38
	v_subrev_u32_e32 v253, s60, v37
	v_alignbit_b32 v254, v254, v252, 31
	v_alignbit_b32 v255, v255, v253, 31
	v_subrev_u32_e32 v252, s60, v1
	v_subrev_u32_e32 v253, s60, v0
	v_alignbit_b32 v254, v254, v252, 31
	v_alignbit_b32 v255, v255, v253, 31
	v_subrev_u32_e32 v252, s60, v3
	v_subrev_u32_e32 v253, s60, v2
	v_alignbit_b32 v254, v254, v252, 31
	v_alignbit_b32 v255, v255, v253, 31
	v_subrev_u32_e32 v252, s60, v5
	v_subrev_u32_e32 v253, s60, v4
	v_alignbit_b32 v254, v254, v252, 31
	v_alignbit_b32 v255, v255, v253, 31
	v_subrev_u32_e32 v252, s60, v7
	v_subrev_u32_e32 v253, s60, v6
	v_alignbit_b32 v254, v254, v252, 31
	v_alignbit_b32 v255, v255, v253, 31
	v_subrev_u32_e32 v252, s60, v9
	v_subrev_u32_e32 v253, s60, v8
	v_alignbit_b32 v254, v254, v252, 31
	v_alignbit_b32 v255, v255, v253, 31
	v_subrev_u32_e32 v252, s60, v11
	v_subrev_u32_e32 v253, s60, v10
	v_alignbit_b32 v254, v254, v252, 31
	v_alignbit_b32 v255, v255, v253, 31
	v_subrev_u32_e32 v252, s60, v13
	v_subrev_u32_e32 v253, s60, v12
	v_alignbit_b32 v254, v254, v252, 31
	v_alignbit_b32 v255, v255, v253, 31
	v_subrev_u32_e32 v252, s60, v15
	v_subrev_u32_e32 v253, s60, v14
	v_alignbit_b32 v254, v254, v252, 31
	v_alignbit_b32 v255, v255, v253, 31
	v_subrev_u32_e32 v252, s60, v17
	v_subrev_u32_e32 v253, s60, v16
	v_alignbit_b32 v254, v254, v252, 31
	v_alignbit_b32 v255, v255, v253, 31
	v_subrev_u32_e32 v252, s60, v19
	v_subrev_u32_e32 v253, s60, v18
	v_alignbit_b32 v254, v254, v252, 31
	v_alignbit_b32 v255, v255, v253, 31
	v_subrev_u32_e32 v252, s60, v21
	v_subrev_u32_e32 v253, s60, v20
	v_alignbit_b32 v254, v254, v252, 31
	v_alignbit_b32 v255, v255, v253, 31
	v_subrev_u32_e32 v252, s60, v23
	v_subrev_u32_e32 v253, s60, v22
	v_alignbit_b32 v254, v254, v252, 31
	v_alignbit_b32 v255, v255, v253, 31
	v_subrev_u32_e32 v252, s60, v25
	v_subrev_u32_e32 v253, s60, v24
	v_alignbit_b32 v254, v254, v252, 31
	v_alignbit_b32 v255, v255, v253, 31
	v_subrev_u32_e32 v252, s60, v27
	v_subrev_u32_e32 v253, s60, v26
	v_alignbit_b32 v254, v254, v252, 31
	v_alignbit_b32 v255, v255, v253, 31
	v_subrev_u32_e32 v252, s60, v29
	v_subrev_u32_e32 v253, s60, v28
	v_alignbit_b32 v254, v254, v252, 31
	v_alignbit_b32 v255, v255, v253, 31
	v_subrev_u32_e32 v252, s60, v31
	v_subrev_u32_e32 v253, s60, v30
	v_alignbit_b32 v254, v254, v252, 31
	v_alignbit_b32 v255, v255, v253, 31
	v_subrev_u32_e32 v252, s60, v33
	v_subrev_u32_e32 v253, s60, v32
	v_alignbit_b32 v254, v254, v252, 31
	v_alignbit_b32 v255, v255, v253, 31
	v_subrev_u32_e32 v252, s60, v35
	v_subrev_u32_e32 v253, s60, v34
	v_alignbit_b32 v254, v254, v252, 31
	v_alignbit_b32 v255, v255, v253, 31
	v_subrev_u32_e32 v252, s60, v40
	v_subrev_u32_e32 v253, s60, v36
	v_alignbit_b32 v254, v254, v252, 31
	v_alignbit_b32 v255, v255, v253, 31
	v_subrev_u32_e32 v252, s60, v43
	v_subrev_u32_e32 v253, s60, v42
	v_alignbit_b32 v254, v254, v252, 31
	v_alignbit_b32 v255, v255, v253, 31
	v_subrev_u32_e32 v252, s60, v46
	v_subrev_u32_e32 v253, s60, v45
	v_alignbit_b32 v254, v254, v252, 31
	v_alignbit_b32 v255, v255, v253, 31
	v_subrev_u32_e32 v252, s60, v48
	v_subrev_u32_e32 v253, s60, v47
	v_alignbit_b32 v254, v254, v252, 31
	v_alignbit_b32 v255, v255, v253, 31
	v_subrev_u32_e32 v252, s60, v50
	v_subrev_u32_e32 v253, s60, v49
	v_alignbit_b32 v254, v254, v252, 31
	v_alignbit_b32 v255, v255, v253, 31
	v_subrev_u32_e32 v252, s60, v52
	v_subrev_u32_e32 v253, s60, v51
	v_alignbit_b32 v254, v254, v252, 31
	v_alignbit_b32 v255, v255, v253, 31
	v_subrev_u32_e32 v252, s60, v54
	v_subrev_u32_e32 v253, s60, v53
	v_alignbit_b32 v254, v254, v252, 31
	v_alignbit_b32 v255, v255, v253, 31
	v_subrev_u32_e32 v252, s60, v56
	v_subrev_u32_e32 v253, s60, v55
	v_alignbit_b32 v254, v254, v252, 31
	v_alignbit_b32 v255, v255, v253, 31
	v_bcnt_u32_b32 v251, v254, 0
	v_bcnt_u32_b32 v251, v255, v251
	s_nop 1
	v_add_u32_dpp v251, v251, v251 quad_perm:[1,0,3,2] row_mask:0xf bank_mask:0xf
	v_mov_b32_e32 v254, 0
	v_mov_b32_e32 v255, 0
	v_add_u32_dpp v251, v251, v251 quad_perm:[2,3,0,1] row_mask:0xf bank_mask:0xf
	s_nop 1
	v_add_u32_dpp v251, v251, v251 row_half_mirror row_mask:0xf bank_mask:0xf
	s_nop 1
	v_add_u32_dpp v251, v251, v251 row_mirror row_mask:0xf bank_mask:0xf
	s_nop 1
	v_add_u32_dpp v251, v251, v251 row_bcast:15 row_mask:0xa bank_mask:0xf
	s_nop 1
	v_add_u32_dpp v251, v251, v251 row_bcast:31 row_mask:0xc bank_mask:0xf
	s_nop 1
	v_readlane_b32 s30, v251, 63
	s_sub_i32 s30, 0xe00, s30
	s_cmpk_lt_u32 s30, 0x100
	s_cselect_b32 s58, s58, s60
	s_cmpk_eq_i32 s30, 0x100
	s_cbranch_scc1 .Lbq_exit
	s_sub_u32 s59, s59, 1
	s_cbranch_scc1 .Lbq_exit
	s_lshl_b32 s60, 1, s59
	s_or_b32 s60, s60, s58
	s_branch .Lbq7_loop
.Lbq6_loop:
	v_subrev_u32_e32 v252, s60, v41
	v_subrev_u32_e32 v253, s60, v39
	v_alignbit_b32 v254, v254, v252, 31
	v_alignbit_b32 v255, v255, v253, 31
	v_subrev_u32_e32 v252, s60, v38
	v_subrev_u32_e32 v253, s60, v37
	v_alignbit_b32 v254, v254, v252, 31
	v_alignbit_b32 v255, v255, v253, 31
	v_subrev_u32_e32 v252, s60, v1
	v_subrev_u32_e32 v253, s60, v0
	v_alignbit_b32 v254, v254, v252, 31
	v_alignbit_b32 v255, v255, v253, 31
	v_subrev_u32_e32 v252, s60, v3
	v_subrev_u32_e32 v253, s60, v2
	v_alignbit_b32 v254, v254, v252, 31
	v_alignbit_b32 v255, v255, v253, 31
	v_subrev_u32_e32 v252, s60, v5
	v_subrev_u32_e32 v253, s60, v4
	v_alignbit_b32 v254, v254, v252, 31
	v_alignbit_b32 v255, v255, v253, 31
	v_subrev_u32_e32 v252, s60, v7
	v_subrev_u32_e32 v253, s60, v6
	v_alignbit_b32 v254, v254, v252, 31
	v_alignbit_b32 v255, v255, v253, 31
	v_subrev_u32_e32 v252, s60, v9
	v_subrev_u32_e32 v253, s60, v8
	v_alignbit_b32 v254, v254, v252, 31
	v_alignbit_b32 v255, v255, v253, 31
	v_subrev_u32_e32 v252, s60, v11
	v_subrev_u32_e32 v253, s60, v10
	v_alignbit_b32 v254, v254, v252, 31
	v_alignbit_b32 v255, v255, v253, 31
	v_subrev_u32_e32 v252, s60, v13
	v_subrev_u32_e32 v253, s60, v12
	v_alignbit_b32 v254, v254, v252, 31
	v_alignbit_b32 v255, v255, v253, 31
	v_subrev_u32_e32 v252, s60, v15
	v_subrev_u32_e32 v253, s60, v14
	v_alignbit_b32 v254, v254, v252, 31
	v_alignbit_b32 v255, v255, v253, 31
	v_subrev_u32_e32 v252, s60, v17
	v_subrev_u32_e32 v253, s60, v16
	v_alignbit_b32 v254, v254, v252, 31
	v_alignbit_b32 v255, v255, v253, 31
	v_subrev_u32_e32 v252, s60, v19
	v_subrev_u32_e32 v253, s60, v18
	v_alignbit_b32 v254, v254, v252, 31
	v_alignbit_b32 v255, v255, v253, 31
	v_subrev_u32_e32 v252, s60, v21
	v_subrev_u32_e32 v253, s60, v20
	v_alignbit_b32 v254, v254, v252, 31
	v_alignbit_b32 v255, v255, v253, 31
	v_subrev_u32_e32 v252, s60, v23
	v_subrev_u32_e32 v253, s60, v22
	v_alignbit_b32 v254, v254, v252, 31
	v_alignbit_b32 v255, v255, v253, 31
	v_subrev_u32_e32 v252, s60, v25
	v_subrev_u32_e32 v253, s60, v24
	v_alignbit_b32 v254, v254, v252, 31
	v_alignbit_b32 v255, v255, v253, 31
	v_subrev_u32_e32 v252, s60, v27
	v_subrev_u32_e32 v253, s60, v26
	v_alignbit_b32 v254, v254, v252, 31
	v_alignbit_b32 v255, v255, v253, 31
	v_subrev_u32_e32 v252, s60, v29
	v_subrev_u32_e32 v253, s60, v28
	v_alignbit_b32 v254, v254, v252, 31
	v_alignbit_b32 v255, v255, v253, 31
	v_subrev_u32_e32 v252, s60, v31
	v_subrev_u32_e32 v253, s60, v30
	v_alignbit_b32 v254, v254, v252, 31
	v_alignbit_b32 v255, v255, v253, 31
	v_subrev_u32_e32 v252, s60, v33
	v_subrev_u32_e32 v253, s60, v32
	v_alignbit_b32 v254, v254, v252, 31
	v_alignbit_b32 v255, v255, v253, 31
	v_subrev_u32_e32 v252, s60, v35
	v_subrev_u32_e32 v253, s60, v34
	v_alignbit_b32 v254, v254, v252, 31
	v_alignbit_b32 v255, v255, v253, 31
	v_subrev_u32_e32 v252, s60, v40
	v_subrev_u32_e32 v253, s60, v36
	v_alignbit_b32 v254, v254, v252, 31
	v_alignbit_b32 v255, v255, v253, 31
	v_subrev_u32_e32 v252, s60, v43
	v_subrev_u32_e32 v253, s60, v42
	v_alignbit_b32 v254, v254, v252, 31
	v_alignbit_b32 v255, v255, v253, 31
	v_subrev_u32_e32 v252, s60, v46
	v_subrev_u32_e32 v253, s60, v45
	v_alignbit_b32 v254, v254, v252, 31
	v_alignbit_b32 v255, v255, v253, 31
	v_subrev_u32_e32 v252, s60, v48
	v_subrev_u32_e32 v253, s60, v47
	v_alignbit_b32 v254, v254, v252, 31
	v_alignbit_b32 v255, v255, v253, 31
	v_bcnt_u32_b32 v251, v254, 0
	v_bcnt_u32_b32 v251, v255, v251
	s_nop 1
	v_add_u32_dpp v251, v251, v251 quad_perm:[1,0,3,2] row_mask:0xf bank_mask:0xf
	v_mov_b32_e32 v254, 0
	v_mov_b32_e32 v255, 0
	v_add_u32_dpp v251, v251, v251 quad_perm:[2,3,0,1] row_mask:0xf bank_mask:0xf
	s_nop 1
	v_add_u32_dpp v251, v251, v251 row_half_mirror row_mask:0xf bank_mask:0xf
	s_nop 1
	v_add_u32_dpp v251, v251, v251 row_mirror row_mask:0xf bank_mask:0xf
	s_nop 1
	v_add_u32_dpp v251, v251, v251 row_bcast:15 row_mask:0xa bank_mask:0xf
	s_nop 1
	v_add_u32_dpp v251, v251, v251 row_bcast:31 row_mask:0xc bank_mask:0xf
	s_nop 1
	v_readlane_b32 s30, v251, 63
	s_sub_i32 s30, 0xc00, s30
	s_cmpk_lt_u32 s30, 0x100
	s_cselect_b32 s58, s58, s60
	s_cmpk_eq_i32 s30, 0x100
	s_cbranch_scc1 .Lbq_exit
	s_sub_u32 s59, s59, 1
	s_cbranch_scc1 .Lbq_exit
	s_lshl_b32 s60, 1, s59
	s_or_b32 s60, s60, s58
	s_branch .Lbq6_loop
.Lbq5_loop:
	v_subrev_u32_e32 v252, s60, v41
	v_subrev_u32_e32 v253, s60, v39
	v_alignbit_b32 v254, v254, v252, 31
	v_alignbit_b32 v255, v255, v253, 31
	v_subrev_u32_e32 v252, s60, v38
	v_subrev_u32_e32 v253, s60, v37
	v_alignbit_b32 v254, v254, v252, 31
	v_alignbit_b32 v255, v255, v253, 31
	v_subrev_u32_e32 v252, s60, v1
	v_subrev_u32_e32 v253, s60, v0
	v_alignbit_b32 v254, v254, v252, 31
	v_alignbit_b32 v255, v255, v253, 31
	v_subrev_u32_e32 v252, s60, v3
	v_subrev_u32_e32 v253, s60, v2
	v_alignbit_b32 v254, v254, v252, 31
	v_alignbit_b32 v255, v255, v253, 31
	v_subrev_u32_e32 v252, s60, v5
	v_subrev_u32_e32 v253, s60, v4
	v_alignbit_b32 v254, v254, v252, 31
	v_alignbit_b32 v255, v255, v253, 31
	v_subrev_u32_e32 v252, s60, v7
	v_subrev_u32_e32 v253, s60, v6
	v_alignbit_b32 v254, v254, v252, 31
	v_alignbit_b32 v255, v255, v253, 31
	v_subrev_u32_e32 v252, s60, v9
	v_subrev_u32_e32 v253, s60, v8
	v_alignbit_b32 v254, v254, v252, 31
	v_alignbit_b32 v255, v255, v253, 31
	v_subrev_u32_e32 v252, s60, v11
	v_subrev_u32_e32 v253, s60, v10
	v_alignbit_b32 v254, v254, v252, 31
	v_alignbit_b32 v255, v255, v253, 31
	v_subrev_u32_e32 v252, s60, v13
	v_subrev_u32_e32 v253, s60, v12
	v_alignbit_b32 v254, v254, v252, 31
	v_alignbit_b32 v255, v255, v253, 31
	v_subrev_u32_e32 v252, s60, v15
	v_subrev_u32_e32 v253, s60, v14
	v_alignbit_b32 v254, v254, v252, 31
	v_alignbit_b32 v255, v255, v253, 31
	v_subrev_u32_e32 v252, s60, v17
	v_subrev_u32_e32 v253, s60, v16
	v_alignbit_b32 v254, v254, v252, 31
	v_alignbit_b32 v255, v255, v253, 31
	v_subrev_u32_e32 v252, s60, v19
	v_subrev_u32_e32 v253, s60, v18
	v_alignbit_b32 v254, v254, v252, 31
	v_alignbit_b32 v255, v255, v253, 31
	v_subrev_u32_e32 v252, s60, v21
	v_subrev_u32_e32 v253, s60, v20
	v_alignbit_b32 v254, v254, v252, 31
	v_alignbit_b32 v255, v255, v253, 31
	v_subrev_u32_e32 v252, s60, v23
	v_subrev_u32_e32 v253, s60, v22
	v_alignbit_b32 v254, v254, v252, 31
	v_alignbit_b32 v255, v255, v253, 31
	v_subrev_u32_e32 v252, s60, v25
	v_subrev_u32_e32 v253, s60, v24
	v_alignbit_b32 v254, v254, v252, 31
	v_alignbit_b32 v255, v255, v253, 31
	v_subrev_u32_e32 v252, s60, v27
	v_subrev_u32_e32 v253, s60, v26
	v_alignbit_b32 v254, v254, v252, 31
	v_alignbit_b32 v255, v255, v253, 31
	v_subrev_u32_e32 v252, s60, v29
	v_subrev_u32_e32 v253, s60, v28
	v_alignbit_b32 v254, v254, v252, 31
	v_alignbit_b32 v255, v255, v253, 31
	v_subrev_u32_e32 v252, s60, v31
	v_subrev_u32_e32 v253, s60, v30
	v_alignbit_b32 v254, v254, v252, 31
	v_alignbit_b32 v255, v255, v253, 31
	v_subrev_u32_e32 v252, s60, v33
	v_subrev_u32_e32 v253, s60, v32
	v_alignbit_b32 v254, v254, v252, 31
	v_alignbit_b32 v255, v255, v253, 31
	v_subrev_u32_e32 v252, s60, v35
	v_subrev_u32_e32 v253, s60, v34
	v_alignbit_b32 v254, v254, v252, 31
	v_alignbit_b32 v255, v255, v253, 31
	v_bcnt_u32_b32 v251, v254, 0
	v_bcnt_u32_b32 v251, v255, v251
	s_nop 1
	v_add_u32_dpp v251, v251, v251 quad_perm:[1,0,3,2] row_mask:0xf bank_mask:0xf
	v_mov_b32_e32 v254, 0
	v_mov_b32_e32 v255, 0
	v_add_u32_dpp v251, v251, v251 quad_perm:[2,3,0,1] row_mask:0xf bank_mask:0xf
	s_nop 1
	v_add_u32_dpp v251, v251, v251 row_half_mirror row_mask:0xf bank_mask:0xf
	s_nop 1
	v_add_u32_dpp v251, v251, v251 row_mirror row_mask:0xf bank_mask:0xf
	s_nop 1
	v_add_u32_dpp v251, v251, v251 row_bcast:15 row_mask:0xa bank_mask:0xf
	s_nop 1
	v_add_u32_dpp v251, v251, v251 row_bcast:31 row_mask:0xc bank_mask:0xf
	s_nop 1
	v_readlane_b32 s30, v251, 63
	s_sub_i32 s30, 0xa00, s30
	s_cmpk_lt_u32 s30, 0x100
	s_cselect_b32 s58, s58, s60
	s_cmpk_eq_i32 s30, 0x100
	s_cbranch_scc1 .Lbq_exit
	s_sub_u32 s59, s59, 1
	s_cbranch_scc1 .Lbq_exit
	s_lshl_b32 s60, 1, s59
	s_or_b32 s60, s60, s58
	s_branch .Lbq5_loop
.Lbq4_loop:
	v_subrev_u32_e32 v252, s60, v41
	v_subrev_u32_e32 v253, s60, v39
	v_alignbit_b32 v254, v254, v252, 31
	v_alignbit_b32 v255, v255, v253, 31
	v_subrev_u32_e32 v252, s60, v38
	v_subrev_u32_e32 v253, s60, v37
	v_alignbit_b32 v254, v254, v252, 31
	v_alignbit_b32 v255, v255, v253, 31
	v_subrev_u32_e32 v252, s60, v1
	v_subrev_u32_e32 v253, s60, v0
	v_alignbit_b32 v254, v254, v252, 31
	v_alignbit_b32 v255, v255, v253, 31
	v_subrev_u32_e32 v252, s60, v3
	v_subrev_u32_e32 v253, s60, v2
	v_alignbit_b32 v254, v254, v252, 31
	v_alignbit_b32 v255, v255, v253, 31
	v_subrev_u32_e32 v252, s60, v5
	v_subrev_u32_e32 v253, s60, v4
	v_alignbit_b32 v254, v254, v252, 31
	v_alignbit_b32 v255, v255, v253, 31
	v_subrev_u32_e32 v252, s60, v7
	v_subrev_u32_e32 v253, s60, v6
	v_alignbit_b32 v254, v254, v252, 31
	v_alignbit_b32 v255, v255, v253, 31
	v_subrev_u32_e32 v252, s60, v9
	v_subrev_u32_e32 v253, s60, v8
	v_alignbit_b32 v254, v254, v252, 31
	v_alignbit_b32 v255, v255, v253, 31
	v_subrev_u32_e32 v252, s60, v11
	v_subrev_u32_e32 v253, s60, v10
	v_alignbit_b32 v254, v254, v252, 31
	v_alignbit_b32 v255, v255, v253, 31
	v_subrev_u32_e32 v252, s60, v13
	v_subrev_u32_e32 v253, s60, v12
	v_alignbit_b32 v254, v254, v252, 31
	v_alignbit_b32 v255, v255, v253, 31
	v_subrev_u32_e32 v252, s60, v15
	v_subrev_u32_e32 v253, s60, v14
	v_alignbit_b32 v254, v254, v252, 31
	v_alignbit_b32 v255, v255, v253, 31
	v_subrev_u32_e32 v252, s60, v17
	v_subrev_u32_e32 v253, s60, v16
	v_alignbit_b32 v254, v254, v252, 31
	v_alignbit_b32 v255, v255, v253, 31
	v_subrev_u32_e32 v252, s60, v19
	v_subrev_u32_e32 v253, s60, v18
	v_alignbit_b32 v254, v254, v252, 31
	v_alignbit_b32 v255, v255, v253, 31
	v_subrev_u32_e32 v252, s60, v21
	v_subrev_u32_e32 v253, s60, v20
	v_alignbit_b32 v254, v254, v252, 31
	v_alignbit_b32 v255, v255, v253, 31
	v_subrev_u32_e32 v252, s60, v23
	v_subrev_u32_e32 v253, s60, v22
	v_alignbit_b32 v254, v254, v252, 31
	v_alignbit_b32 v255, v255, v253, 31
	v_subrev_u32_e32 v252, s60, v25
	v_subrev_u32_e32 v253, s60, v24
	v_alignbit_b32 v254, v254, v252, 31
	v_alignbit_b32 v255, v255, v253, 31
	v_subrev_u32_e32 v252, s60, v27
	v_subrev_u32_e32 v253, s60, v26
	v_alignbit_b32 v254, v254, v252, 31
	v_alignbit_b32 v255, v255, v253, 31
	v_bcnt_u32_b32 v251, v254, 0
	v_bcnt_u32_b32 v251, v255, v251
	s_nop 1
	v_add_u32_dpp v251, v251, v251 quad_perm:[1,0,3,2] row_mask:0xf bank_mask:0xf
	v_mov_b32_e32 v254, 0
	v_mov_b32_e32 v255, 0
	v_add_u32_dpp v251, v251, v251 quad_perm:[2,3,0,1] row_mask:0xf bank_mask:0xf
	s_nop 1
	v_add_u32_dpp v251, v251, v251 row_half_mirror row_mask:0xf bank_mask:0xf
	s_nop 1
	v_add_u32_dpp v251, v251, v251 row_mirror row_mask:0xf bank_mask:0xf
	s_nop 1
	v_add_u32_dpp v251, v251, v251 row_bcast:15 row_mask:0xa bank_mask:0xf
	s_nop 1
	v_add_u32_dpp v251, v251, v251 row_bcast:31 row_mask:0xc bank_mask:0xf
	s_nop 1
	v_readlane_b32 s30, v251, 63
	s_sub_i32 s30, 0x800, s30
	s_cmpk_lt_u32 s30, 0x100
	s_cselect_b32 s58, s58, s60
	s_cmpk_eq_i32 s30, 0x100
	s_cbranch_scc1 .Lbq_exit
	s_sub_u32 s59, s59, 1
	s_cbranch_scc1 .Lbq_exit
	s_lshl_b32 s60, 1, s59
	s_or_b32 s60, s60, s58
	s_branch .Lbq4_loop
.Lbq3_loop:
	v_subrev_u32_e32 v252, s60, v41
	v_subrev_u32_e32 v253, s60, v39
	v_alignbit_b32 v254, v254, v252, 31
	v_alignbit_b32 v255, v255, v253, 31
	v_subrev_u32_e32 v252, s60, v38
	v_subrev_u32_e32 v253, s60, v37
	v_alignbit_b32 v254, v254, v252, 31
	v_alignbit_b32 v255, v255, v253, 31
	v_subrev_u32_e32 v252, s60, v1
	v_subrev_u32_e32 v253, s60, v0
	v_alignbit_b32 v254, v254, v252, 31
	v_alignbit_b32 v255, v255, v253, 31
	v_subrev_u32_e32 v252, s60, v3
	v_subrev_u32_e32 v253, s60, v2
	v_alignbit_b32 v254, v254, v252, 31
	v_alignbit_b32 v255, v255, v253, 31
	v_subrev_u32_e32 v252, s60, v5
	v_subrev_u32_e32 v253, s60, v4
	v_alignbit_b32 v254, v254, v252, 31
	v_alignbit_b32 v255, v255, v253, 31
	v_subrev_u32_e32 v252, s60, v7
	v_subrev_u32_e32 v253, s60, v6
	v_alignbit_b32 v254, v254, v252, 31
	v_alignbit_b32 v255, v255, v253, 31
	v_subrev_u32_e32 v252, s60, v9
	v_subrev_u32_e32 v253, s60, v8
	v_alignbit_b32 v254, v254, v252, 31
	v_alignbit_b32 v255, v255, v253, 31
	v_subrev_u32_e32 v252, s60, v11
	v_subrev_u32_e32 v253, s60, v10
	v_alignbit_b32 v254, v254, v252, 31
	v_alignbit_b32 v255, v255, v253, 31
	v_subrev_u32_e32 v252, s60, v13
	v_subrev_u32_e32 v253, s60, v12
	v_alignbit_b32 v254, v254, v252, 31
	v_alignbit_b32 v255, v255, v253, 31
	v_subrev_u32_e32 v252, s60, v15
	v_subrev_u32_e32 v253, s60, v14
	v_alignbit_b32 v254, v254, v252, 31
	v_alignbit_b32 v255, v255, v253, 31
	v_subrev_u32_e32 v252, s60, v17
	v_subrev_u32_e32 v253, s60, v16
	v_alignbit_b32 v254, v254, v252, 31
	v_alignbit_b32 v255, v255, v253, 31
	v_subrev_u32_e32 v252, s60, v19
	v_subrev_u32_e32 v253, s60, v18
	v_alignbit_b32 v254, v254, v252, 31
	v_alignbit_b32 v255, v255, v253, 31
	v_bcnt_u32_b32 v251, v254, 0
	v_bcnt_u32_b32 v251, v255, v251
	s_nop 1
	v_add_u32_dpp v251, v251, v251 quad_perm:[1,0,3,2] row_mask:0xf bank_mask:0xf
	v_mov_b32_e32 v254, 0
	v_mov_b32_e32 v255, 0
	v_add_u32_dpp v251, v251, v251 quad_perm:[2,3,0,1] row_mask:0xf bank_mask:0xf
	s_nop 1
	v_add_u32_dpp v251, v251, v251 row_half_mirror row_mask:0xf bank_mask:0xf
	s_nop 1
	v_add_u32_dpp v251, v251, v251 row_mirror row_mask:0xf bank_mask:0xf
	s_nop 1
	v_add_u32_dpp v251, v251, v251 row_bcast:15 row_mask:0xa bank_mask:0xf
	s_nop 1
	v_add_u32_dpp v251, v251, v251 row_bcast:31 row_mask:0xc bank_mask:0xf
	s_nop 1
	v_readlane_b32 s30, v251, 63
	s_sub_i32 s30, 0x600, s30
	s_cmpk_lt_u32 s30, 0x100
	s_cselect_b32 s58, s58, s60
	s_cmpk_eq_i32 s30, 0x100
	s_cbranch_scc1 .Lbq_exit
	s_sub_u32 s59, s59, 1
	s_cbranch_scc1 .Lbq_exit
	s_lshl_b32 s60, 1, s59
	s_or_b32 s60, s60, s58
	s_branch .Lbq3_loop
.Lbq2_loop:
	v_subrev_u32_e32 v252, s60, v41
	v_subrev_u32_e32 v253, s60, v39
	v_alignbit_b32 v254, v254, v252, 31
	v_alignbit_b32 v255, v255, v253, 31
	v_subrev_u32_e32 v252, s60, v38
	v_subrev_u32_e32 v253, s60, v37
	v_alignbit_b32 v254, v254, v252, 31
	v_alignbit_b32 v255, v255, v253, 31
	v_subrev_u32_e32 v252, s60, v1
	v_subrev_u32_e32 v253, s60, v0
	v_alignbit_b32 v254, v254, v252, 31
	v_alignbit_b32 v255, v255, v253, 31
	v_subrev_u32_e32 v252, s60, v3
	v_subrev_u32_e32 v253, s60, v2
	v_alignbit_b32 v254, v254, v252, 31
	v_alignbit_b32 v255, v255, v253, 31
	v_subrev_u32_e32 v252, s60, v5
	v_subrev_u32_e32 v253, s60, v4
	v_alignbit_b32 v254, v254, v252, 31
	v_alignbit_b32 v255, v255, v253, 31
	v_subrev_u32_e32 v252, s60, v7
	v_subrev_u32_e32 v253, s60, v6
	v_alignbit_b32 v254, v254, v252, 31
	v_alignbit_b32 v255, v255, v253, 31
	v_subrev_u32_e32 v252, s60, v9
	v_subrev_u32_e32 v253, s60, v8
	v_alignbit_b32 v254, v254, v252, 31
	v_alignbit_b32 v255, v255, v253, 31
	v_subrev_u32_e32 v252, s60, v11
	v_subrev_u32_e32 v253, s60, v10
	v_alignbit_b32 v254, v254, v252, 31
	v_alignbit_b32 v255, v255, v253, 31
	v_bcnt_u32_b32 v251, v254, 0
	v_bcnt_u32_b32 v251, v255, v251
	s_nop 1
	v_add_u32_dpp v251, v251, v251 quad_perm:[1,0,3,2] row_mask:0xf bank_mask:0xf
	v_mov_b32_e32 v254, 0
	v_mov_b32_e32 v255, 0
	v_add_u32_dpp v251, v251, v251 quad_perm:[2,3,0,1] row_mask:0xf bank_mask:0xf
	s_nop 1
	v_add_u32_dpp v251, v251, v251 row_half_mirror row_mask:0xf bank_mask:0xf
	s_nop 1
	v_add_u32_dpp v251, v251, v251 row_mirror row_mask:0xf bank_mask:0xf
	s_nop 1
	v_add_u32_dpp v251, v251, v251 row_bcast:15 row_mask:0xa bank_mask:0xf
	s_nop 1
	v_add_u32_dpp v251, v251, v251 row_bcast:31 row_mask:0xc bank_mask:0xf
	s_nop 1
	v_readlane_b32 s30, v251, 63
	s_sub_i32 s30, 0x400, s30
	s_cmpk_lt_u32 s30, 0x100
	s_cselect_b32 s58, s58, s60
	s_cmpk_eq_i32 s30, 0x100
	s_cbranch_scc1 .Lbq_exit
	s_sub_u32 s59, s59, 1
	s_cbranch_scc1 .Lbq_exit
	s_lshl_b32 s60, 1, s59
	s_or_b32 s60, s60, s58
	s_branch .Lbq2_loop
.Lbq1_loop:
	v_subrev_u32_e32 v252, s60, v41
	v_subrev_u32_e32 v253, s60, v39
	v_alignbit_b32 v254, v254, v252, 31
	v_alignbit_b32 v255, v255, v253, 31
	v_subrev_u32_e32 v252, s60, v38
	v_subrev_u32_e32 v253, s60, v37
	v_alignbit_b32 v254, v254, v252, 31
	v_alignbit_b32 v255, v255, v253, 31
	v_subrev_u32_e32 v252, s60, v1
	v_subrev_u32_e32 v253, s60, v0
	v_alignbit_b32 v254, v254, v252, 31
	v_alignbit_b32 v255, v255, v253, 31
	v_subrev_u32_e32 v252, s60, v3
	v_subrev_u32_e32 v253, s60, v2
	v_alignbit_b32 v254, v254, v252, 31
	v_alignbit_b32 v255, v255, v253, 31
	v_bcnt_u32_b32 v251, v254, 0
	v_bcnt_u32_b32 v251, v255, v251
	s_nop 1
	v_add_u32_dpp v251, v251, v251 quad_perm:[1,0,3,2] row_mask:0xf bank_mask:0xf
	v_mov_b32_e32 v254, 0
	v_mov_b32_e32 v255, 0
	v_add_u32_dpp v251, v251, v251 quad_perm:[2,3,0,1] row_mask:0xf bank_mask:0xf
	s_nop 1
	v_add_u32_dpp v251, v251, v251 row_half_mirror row_mask:0xf bank_mask:0xf
	s_nop 1
	v_add_u32_dpp v251, v251, v251 row_mirror row_mask:0xf bank_mask:0xf
	s_nop 1
	v_add_u32_dpp v251, v251, v251 row_bcast:15 row_mask:0xa bank_mask:0xf
	s_nop 1
	v_add_u32_dpp v251, v251, v251 row_bcast:31 row_mask:0xc bank_mask:0xf
	s_nop 1
	v_readlane_b32 s30, v251, 63
	s_sub_i32 s30, 0x200, s30
	s_cmpk_lt_u32 s30, 0x100
	s_cselect_b32 s58, s58, s60
	s_cmpk_eq_i32 s30, 0x100
	s_cbranch_scc1 .Lbq_exit
	s_sub_u32 s59, s59, 1
	s_cbranch_scc1 .Lbq_exit
	s_lshl_b32 s60, 1, s59
	s_or_b32 s60, s60, s58
	s_branch .Lbq1_loop

.Lg4_skip:
	ds_read_b64 v[68:69], v220 offset:18432
	ds_read_b64 v[70:71], v221 offset:18432
	ds_read_b64 v[84:85], v224 offset:55296
	ds_read_b64 v[86:87], v225 offset:55296
	ds_read_b64 v[88:89], v224 offset:57344
	ds_read_b64 v[90:91], v225 offset:57344
	ds_read_b64 v[92:93], v224 offset:59392
	ds_read_b64 v[94:95], v225 offset:59392
	ds_read_b64 v[130:131], v224 offset:61440
	ds_read_b64 v[132:133], v225 offset:61440
	ds_read_b64 v[72:73], v220 offset:20480
	ds_read_b64 v[74:75], v221 offset:20480
	ds_read_b64 v[76:77], v220 offset:22528
	ds_read_b64 v[78:79], v221 offset:22528
	s_waitcnt lgkmcnt(12)
	s_waitcnt lgkmcnt(10)
	v_mfma_f32_16x16x32_bf16 v[12:15], v[68:71], v[84:87], v[12:15]
	ds_read_b64 v[80:81], v220 offset:24576
	ds_read_b64 v[82:83], v221 offset:24576
	ds_read_b64 v[134:135], v222 offset:18432
	ds_read_b64 v[136:137], v223 offset:18432
	s_waitcnt lgkmcnt(12)
	v_mfma_f32_16x16x32_bf16 v[32:35], v[68:71], v[88:91], v[32:35]
	ds_read_b64 v[150:151], v226 offset:55296
	ds_read_b64 v[152:153], v227 offset:55296
	s_waitcnt lgkmcnt(12)
	v_mfma_f32_16x16x32_bf16 v[52:55], v[68:71], v[92:95], v[52:55]
	ds_read_b64 v[154:155], v226 offset:57344
	ds_read_b64 v[156:157], v227 offset:57344
	s_waitcnt lgkmcnt(12)
	v_mfma_f32_16x16x32_bf16 v[56:59], v[68:71], v[130:133], v[56:59]
	ds_read_b64 v[170:171], v226 offset:59392
	ds_read_b64 v[172:173], v227 offset:59392
	s_waitcnt lgkmcnt(12)
	v_mfma_f32_16x16x32_bf16 v[36:39], v[72:75], v[84:87], v[36:39]
	ds_read_b64 v[174:175], v226 offset:61440
	ds_read_b64 v[176:177], v227 offset:61440
	v_mfma_f32_16x16x32_bf16 v[40:43], v[72:75], v[88:91], v[40:43]
	v_mfma_f32_16x16x32_bf16 v[44:47], v[72:75], v[92:95], v[44:47]
	v_mfma_f32_16x16x32_bf16 v[48:51], v[72:75], v[130:133], v[48:51]
	s_waitcnt lgkmcnt(12)
	v_mfma_f32_16x16x32_bf16 v[24:27], v[76:79], v[84:87], v[24:27]
	ds_read_b64 v[138:139], v222 offset:20480
	ds_read_b64 v[140:141], v223 offset:20480
	v_mfma_f32_16x16x32_bf16 v[20:23], v[76:79], v[88:91], v[20:23]
	v_mfma_f32_16x16x32_bf16 v[16:19], v[76:79], v[92:95], v[16:19]
	v_mfma_f32_16x16x32_bf16 v[28:31], v[76:79], v[130:133], v[28:31]
	s_waitcnt lgkmcnt(12)
	v_mfma_f32_16x16x32_bf16 v[0:3], v[80:83], v[84:87], v[0:3]
	ds_read_b64 v[142:143], v222 offset:22528
	ds_read_b64 v[144:145], v223 offset:22528
	v_mfma_f32_16x16x32_bf16 v[4:7], v[80:83], v[88:91], v[4:7]
	v_mfma_f32_16x16x32_bf16 v[8:11], v[80:83], v[92:95], v[8:11]
	v_mfma_f32_16x16x32_bf16 v[60:63], v[80:83], v[130:133], v[60:63]
	s_waitcnt lgkmcnt(12)
	s_waitcnt lgkmcnt(10)
	v_mfma_f32_16x16x32_bf16 v[12:15], v[134:137], v[150:153], v[12:15]
	ds_read_b64 v[146:147], v222 offset:24576
	ds_read_b64 v[148:149], v223 offset:24576
	s_waitcnt lgkmcnt(10)
	v_mfma_f32_16x16x32_bf16 v[32:35], v[134:137], v[154:157], v[32:35]
	s_waitcnt lgkmcnt(8)
	v_mfma_f32_16x16x32_bf16 v[52:55], v[134:137], v[170:173], v[52:55]
	s_waitcnt lgkmcnt(6)
	v_mfma_f32_16x16x32_bf16 v[56:59], v[134:137], v[174:177], v[56:59]
	s_waitcnt lgkmcnt(4)
	v_mfma_f32_16x16x32_bf16 v[36:39], v[138:141], v[150:153], v[36:39]
	v_mfma_f32_16x16x32_bf16 v[40:43], v[138:141], v[154:157], v[40:43]
	v_mfma_f32_16x16x32_bf16 v[44:47], v[138:141], v[170:173], v[44:47]
	v_mfma_f32_16x16x32_bf16 v[48:51], v[138:141], v[174:177], v[48:51]
	s_waitcnt lgkmcnt(2)
	v_mfma_f32_16x16x32_bf16 v[24:27], v[142:145], v[150:153], v[24:27]
	v_mfma_f32_16x16x32_bf16 v[20:23], v[142:145], v[154:157], v[20:23]
	v_mfma_f32_16x16x32_bf16 v[16:19], v[142:145], v[170:173], v[16:19]
	v_mfma_f32_16x16x32_bf16 v[28:31], v[142:145], v[174:177], v[28:31]
	s_waitcnt lgkmcnt(0)
	v_mfma_f32_16x16x32_bf16 v[0:3], v[146:149], v[150:153], v[0:3]
	v_mfma_f32_16x16x32_bf16 v[4:7], v[146:149], v[154:157], v[4:7]
	v_mfma_f32_16x16x32_bf16 v[8:11], v[146:149], v[170:173], v[8:11]
	v_mfma_f32_16x16x32_bf16 v[60:63], v[146:149], v[174:177], v[60:63]
	s_add_i32 s21, s21, 1
	s_cmp_lg_u32 s21, 8
	s_waitcnt vmcnt(0)
	s_barrier
	s_cbranch_scc1 .Lg4_loop
	s_setprio 0
	v_readfirstlane_b32 s0, v104
	s_and_b32 s10, s0, 64
	s_lshr_b32 s0, s0, 1
	s_and_b32 s12, s0, 0x7fffffc0
	s_lshl_b32 s0, s8, 2
	s_add_u32 s8, s36, s0
	s_waitcnt vmcnt(6)
	v_or_b32_e32 v64, s9, v112
	s_addc_u32 s9, s37, 0
	s_lshl_b32 s10, s10, 2
	s_add_u32 s8, s8, s10
	v_add_u32_e32 v116, s12, v64
	s_addc_u32 s9, s9, 0
	v_mov_b32_e32 v115, v117
	v_lshl_add_u64 v[64:65], s[8:9], 0, v[114:115]
	v_lshlrev_b64 v[66:67], 12, v[116:117]
	v_lshl_add_u64 v[68:69], v[64:65], 0, v[66:67]
	v_or_b32_e32 v70, 0x1000, v66
	v_mov_b32_e32 v71, v67
	s_waitcnt vmcnt(5)
	v_lshl_add_u64 v[72:73], v[64:65], 0, v[70:71]
	global_load_dword v106, v[68:69], off
	global_load_dword v107, v[68:69], off offset:64
	global_load_dword v109, v[68:69], off offset:128
	global_load_dword v111, v[68:69], off offset:192
	global_load_dword v113, v[72:73], off
	global_load_dword v116, v[72:73], off offset:64
	global_load_dword v118, v[72:73], off offset:128
	global_load_dword v119, v[72:73], off offset:192
	v_or_b32_e32 v68, 0x2000, v66
	v_mov_b32_e32 v69, v67
	v_lshl_add_u64 v[72:73], v[64:65], 0, v[68:69]
	v_or_b32_e32 v74, 0x3000, v66
	v_mov_b32_e32 v75, v67
	s_waitcnt vmcnt(9)
	v_lshl_add_u64 v[76:77], v[64:65], 0, v[74:75]
	global_load_dword v120, v[72:73], off
	global_load_dword v121, v[72:73], off offset:64
	global_load_dword v122, v[72:73], off offset:128
	global_load_dword v123, v[72:73], off offset:192
	global_load_dword v124, v[76:77], off
	global_load_dword v125, v[76:77], off offset:64
	global_load_dword v126, v[76:77], off offset:128
	global_load_dword v127, v[76:77], off offset:192
	v_or_b32_e32 v72, 0x10000, v66
	v_mov_b32_e32 v73, v67
	v_lshl_add_u64 v[76:77], v[64:65], 0, v[72:73]
	v_or_b32_e32 v78, 0x11000, v66
	v_mov_b32_e32 v79, v67
	v_lshl_add_u64 v[80:81], v[64:65], 0, v[78:79]
	global_load_dword v128, v[76:77], off
	global_load_dword v129, v[76:77], off offset:64
	global_load_dword v130, v[76:77], off offset:128
	global_load_dword v131, v[76:77], off offset:192
	global_load_dword v132, v[80:81], off
	global_load_dword v133, v[80:81], off offset:64
	global_load_dword v134, v[80:81], off offset:128
	global_load_dword v135, v[80:81], off offset:192
	v_or_b32_e32 v76, 0x12000, v66
	v_mov_b32_e32 v77, v67
	v_lshl_add_u64 v[80:81], v[64:65], 0, v[76:77]
	v_or_b32_e32 v82, 0x13000, v66
	v_mov_b32_e32 v83, v67
	v_lshl_add_u64 v[84:85], v[64:65], 0, v[82:83]
	global_load_dword v136, v[80:81], off
	global_load_dword v137, v[80:81], off offset:64
	global_load_dword v138, v[80:81], off offset:128
	global_load_dword v139, v[80:81], off offset:192
	global_load_dword v140, v[84:85], off
	global_load_dword v141, v[84:85], off offset:64
	global_load_dword v142, v[84:85], off offset:128
	global_load_dword v143, v[84:85], off offset:192
	v_or_b32_e32 v80, 0x20000, v66
	v_mov_b32_e32 v81, v67
	v_lshl_add_u64 v[84:85], v[64:65], 0, v[80:81]
	v_or_b32_e32 v86, 0x21000, v66
	v_mov_b32_e32 v87, v67
	v_lshl_add_u64 v[88:89], v[64:65], 0, v[86:87]
	global_load_dword v144, v[84:85], off
	global_load_dword v145, v[84:85], off offset:64
	global_load_dword v146, v[84:85], off offset:128
	global_load_dword v147, v[84:85], off offset:192
	global_load_dword v148, v[88:89], off
	global_load_dword v149, v[88:89], off offset:64
	global_load_dword v150, v[88:89], off offset:128
	global_load_dword v151, v[88:89], off offset:192
	v_or_b32_e32 v84, 0x22000, v66
	v_mov_b32_e32 v85, v67
	v_lshl_add_u64 v[88:89], v[64:65], 0, v[84:85]
	v_or_b32_e32 v90, 0x23000, v66
	v_mov_b32_e32 v91, v67
	s_waitcnt vmcnt(40)
	v_lshl_add_u64 v[92:93], v[64:65], 0, v[90:91]
	global_load_dword v152, v[88:89], off
	global_load_dword v153, v[88:89], off offset:64
	global_load_dword v154, v[88:89], off offset:128
	global_load_dword v155, v[88:89], off offset:192
	global_load_dword v156, v[92:93], off
	global_load_dword v157, v[92:93], off offset:64
	global_load_dword v158, v[92:93], off offset:128
	global_load_dword v159, v[92:93], off offset:192
	v_or_b32_e32 v88, 0x30000, v66
	v_mov_b32_e32 v89, v67
	v_lshl_add_u64 v[92:93], v[64:65], 0, v[88:89]
	v_or_b32_e32 v94, 0x31000, v66
	v_mov_b32_e32 v95, v67
	v_lshl_add_u64 v[100:101], v[64:65], 0, v[94:95]
	global_load_dword v160, v[92:93], off
	global_load_dword v161, v[92:93], off offset:64
	global_load_dword v162, v[92:93], off offset:128
	global_load_dword v163, v[92:93], off offset:192
	global_load_dword v164, v[100:101], off
	global_load_dword v165, v[100:101], off offset:64
	global_load_dword v166, v[100:101], off offset:128
	global_load_dword v167, v[100:101], off offset:192
	v_or_b32_e32 v92, 0x32000, v66
	v_mov_b32_e32 v93, v67
	v_lshl_add_u64 v[100:101], v[64:65], 0, v[92:93]
	v_or_b32_e32 v102, 0x33000, v66
	v_mov_b32_e32 v103, v67
	v_lshl_add_u64 v[64:65], v[64:65], 0, v[102:103]
	global_load_dword v168, v[100:101], off
	global_load_dword v169, v[100:101], off offset:64
	global_load_dword v170, v[100:101], off offset:128
	s_nop 0
	global_load_dword v100, v[100:101], off offset:192
	s_nop 0
	global_load_dword v101, v[64:65], off
	global_load_dword v171, v[64:65], off offset:64
	global_load_dword v172, v[64:65], off offset:128
	global_load_dword v173, v[64:65], off offset:192
	s_add_u32 s0, s52, s0
	s_addc_u32 s9, s53, 0
	s_add_u32 s8, s0, s10
	s_addc_u32 s9, s9, 0
	v_lshl_add_u64 v[64:65], s[8:9], 0, v[114:115]
	v_lshl_add_u64 v[66:67], v[64:65], 0, v[66:67]
	s_waitcnt vmcnt(62)
	v_add_f32_e32 v12, v12, v106
	global_store_dword v[66:67], v12, off
	v_add_f32_e32 v12, v32, v107
	global_store_dword v[66:67], v12, off offset:64
	s_waitcnt vmcnt(62)
	v_add_f32_e32 v12, v52, v109
	global_store_dword v[66:67], v12, off offset:128
	v_add_f32_e32 v12, v56, v111
	global_store_dword v[66:67], v12, off offset:192
	v_lshl_add_u64 v[66:67], v[64:65], 0, v[70:71]
	s_waitcnt vmcnt(62)
	v_add_f32_e32 v12, v13, v113
	global_store_dword v[66:67], v12, off
	v_add_f32_e32 v12, v33, v116
	global_store_dword v[66:67], v12, off offset:64
	s_waitcnt vmcnt(62)
	v_add_f32_e32 v12, v53, v118
	global_store_dword v[66:67], v12, off offset:128
	v_add_f32_e32 v12, v57, v119
	global_store_dword v[66:67], v12, off offset:192
	v_lshl_add_u64 v[12:13], v[64:65], 0, v[68:69]
	s_waitcnt vmcnt(62)
	v_add_f32_e32 v14, v14, v120
	global_store_dword v[12:13], v14, off
	v_add_f32_e32 v14, v34, v121
	global_store_dword v[12:13], v14, off offset:64
	s_waitcnt vmcnt(62)
	v_add_f32_e32 v14, v54, v122
	global_store_dword v[12:13], v14, off offset:128
	v_add_f32_e32 v14, v58, v123
	global_store_dword v[12:13], v14, off offset:192
	v_lshl_add_u64 v[12:13], v[64:65], 0, v[74:75]
	s_waitcnt vmcnt(62)
	v_add_f32_e32 v14, v15, v124
	global_store_dword v[12:13], v14, off
	v_add_f32_e32 v14, v35, v125
	global_store_dword v[12:13], v14, off offset:64
	s_waitcnt vmcnt(62)
	v_add_f32_e32 v14, v55, v126
	global_store_dword v[12:13], v14, off offset:128
	v_add_f32_e32 v14, v59, v127
	global_store_dword v[12:13], v14, off offset:192
	v_lshl_add_u64 v[12:13], v[64:65], 0, v[72:73]
	s_waitcnt vmcnt(62)
	v_add_f32_e32 v14, v36, v128
	global_store_dword v[12:13], v14, off
	v_add_f32_e32 v14, v40, v129
	global_store_dword v[12:13], v14, off offset:64
	s_waitcnt vmcnt(62)
	v_add_f32_e32 v14, v44, v130
	global_store_dword v[12:13], v14, off offset:128
	v_add_f32_e32 v14, v48, v131
	global_store_dword v[12:13], v14, off offset:192
	v_lshl_add_u64 v[12:13], v[64:65], 0, v[78:79]
	s_waitcnt vmcnt(62)
	v_add_f32_e32 v14, v37, v132
	global_store_dword v[12:13], v14, off
	v_add_f32_e32 v14, v41, v133
	global_store_dword v[12:13], v14, off offset:64
	s_waitcnt vmcnt(62)
	v_add_f32_e32 v14, v45, v134
	global_store_dword v[12:13], v14, off offset:128
	v_add_f32_e32 v14, v49, v135
	global_store_dword v[12:13], v14, off offset:192
	v_lshl_add_u64 v[12:13], v[64:65], 0, v[76:77]
	s_waitcnt vmcnt(62)
	v_add_f32_e32 v14, v38, v136
	global_store_dword v[12:13], v14, off
	v_add_f32_e32 v14, v42, v137
	global_store_dword v[12:13], v14, off offset:64
	s_waitcnt vmcnt(62)
	v_add_f32_e32 v14, v46, v138
	global_store_dword v[12:13], v14, off offset:128
	v_add_f32_e32 v14, v50, v139
	global_store_dword v[12:13], v14, off offset:192
	v_lshl_add_u64 v[12:13], v[64:65], 0, v[82:83]
	s_waitcnt vmcnt(62)
	v_add_f32_e32 v14, v39, v140
	global_store_dword v[12:13], v14, off
	v_add_f32_e32 v14, v43, v141
	global_store_dword v[12:13], v14, off offset:64
	s_waitcnt vmcnt(62)
	v_add_f32_e32 v14, v47, v142
	global_store_dword v[12:13], v14, off offset:128
	v_add_f32_e32 v14, v51, v143
	global_store_dword v[12:13], v14, off offset:192
	v_lshl_add_u64 v[12:13], v[64:65], 0, v[80:81]
	s_waitcnt vmcnt(62)
	v_add_f32_e32 v14, v24, v144
	global_store_dword v[12:13], v14, off
	v_add_f32_e32 v14, v20, v145
	global_store_dword v[12:13], v14, off offset:64
	s_waitcnt vmcnt(62)
	v_add_f32_e32 v14, v16, v146
	global_store_dword v[12:13], v14, off offset:128
	v_add_f32_e32 v14, v28, v147
	global_store_dword v[12:13], v14, off offset:192
	v_lshl_add_u64 v[12:13], v[64:65], 0, v[86:87]
	s_waitcnt vmcnt(62)
	v_add_f32_e32 v14, v25, v148
	global_store_dword v[12:13], v14, off
	v_add_f32_e32 v14, v21, v149
	global_store_dword v[12:13], v14, off offset:64
	s_waitcnt vmcnt(62)
	v_add_f32_e32 v14, v17, v150
	global_store_dword v[12:13], v14, off offset:128
	v_add_f32_e32 v14, v29, v151
	global_store_dword v[12:13], v14, off offset:192
	v_lshl_add_u64 v[12:13], v[64:65], 0, v[84:85]
	s_waitcnt vmcnt(62)
	v_add_f32_e32 v14, v26, v152
	global_store_dword v[12:13], v14, off
	v_add_f32_e32 v14, v22, v153
	global_store_dword v[12:13], v14, off offset:64
	s_waitcnt vmcnt(62)
	v_add_f32_e32 v14, v18, v154
	global_store_dword v[12:13], v14, off offset:128
	v_add_f32_e32 v14, v30, v155
	global_store_dword v[12:13], v14, off offset:192
	v_lshl_add_u64 v[12:13], v[64:65], 0, v[90:91]
	s_waitcnt vmcnt(62)
	v_add_f32_e32 v14, v27, v156
	global_store_dword v[12:13], v14, off
	v_add_f32_e32 v14, v23, v157
	global_store_dword v[12:13], v14, off offset:64
	s_waitcnt vmcnt(62)
	v_add_f32_e32 v14, v19, v158
	global_store_dword v[12:13], v14, off offset:128
	v_add_f32_e32 v14, v31, v159
	global_store_dword v[12:13], v14, off offset:192
	v_lshl_add_u64 v[12:13], v[64:65], 0, v[88:89]
	s_waitcnt vmcnt(62)
	v_add_f32_e32 v0, v0, v160
	global_store_dword v[12:13], v0, off
	v_add_f32_e32 v0, v4, v161
	global_store_dword v[12:13], v0, off offset:64
	s_waitcnt vmcnt(62)
	v_add_f32_e32 v0, v8, v162
	global_store_dword v[12:13], v0, off offset:128
	v_add_f32_e32 v0, v60, v163
	global_store_dword v[12:13], v0, off offset:192
	v_lshl_add_u64 v[12:13], v[64:65], 0, v[94:95]
	s_waitcnt vmcnt(62)
	v_add_f32_e32 v0, v1, v164
	global_store_dword v[12:13], v0, off
	v_add_f32_e32 v0, v5, v165
	global_store_dword v[12:13], v0, off offset:64
	s_waitcnt vmcnt(62)
	v_add_f32_e32 v0, v9, v166
	global_store_dword v[12:13], v0, off offset:128
	v_add_f32_e32 v0, v61, v167
	global_store_dword v[12:13], v0, off offset:192
	v_lshl_add_u64 v[0:1], v[64:65], 0, v[92:93]
	s_waitcnt vmcnt(62)
	v_add_f32_e32 v2, v2, v168
	global_store_dword v[0:1], v2, off
	v_add_f32_e32 v2, v6, v169
	global_store_dword v[0:1], v2, off offset:64
	s_waitcnt vmcnt(62)
	v_add_f32_e32 v2, v10, v170
	global_store_dword v[0:1], v2, off offset:128
	v_add_f32_e32 v2, v62, v100
	global_store_dword v[0:1], v2, off offset:192
	v_lshl_add_u64 v[0:1], v[64:65], 0, v[102:103]
	s_waitcnt vmcnt(62)
	v_add_f32_e32 v2, v3, v101
	global_store_dword v[0:1], v2, off
	v_add_f32_e32 v2, v7, v171
	global_store_dword v[0:1], v2, off offset:64
	s_waitcnt vmcnt(62)
	v_add_f32_e32 v2, v11, v172
	global_store_dword v[0:1], v2, off offset:128
	v_add_f32_e32 v2, v63, v173
	global_store_dword v[0:1], v2, off offset:192
	s_branch .LBB0_892
